# P16: WGs >=128 (one tile fewer) start ~5us late so their SwiGLU epilogues overlap the other half's main loops
# speedup vs baseline: 1.0042x; 1.0042x over previous
.Llb_after_13:
.LBB0_1965:
	s_cmp_lt_i32 s78, 17
	s_cselect_b64 s[0:1], -1, 0
	s_and_b64 s[4:5], s[0:1], s[4:5]
	s_andn2_b64 vcc, exec, s[4:5]
	s_cbranch_vccnz .LBB0_1982
	s_cmpk_gt_i32 s2, 0x57f
	v_readfirstlane_b32 s5, v185
	s_cbranch_scc1 .LBB0_1982
	s_cmpk_lt_u32 s2, 0x80
	s_cbranch_scc1 .Lstg_1967
	s_sleep 127
	s_sleep 50
.Lstg_1967:
	v_lshrrev_b32_e32 v0, 5, v185
	v_lshrrev_b32_e32 v2, 1, v185
	v_and_b32_e32 v0, 4, v0
	s_waitcnt lgkmcnt(0)
	v_bfe_u32 v1, v185, 2, 2
	v_and_b32_e32 v11, 24, v2
	v_or3_b32 v0, v0, v1, v11
	v_lshlrev_b32_e32 v1, 4, v185
	v_add_u32_e32 v8, 0x2000, v1
	v_lshrrev_b32_e32 v2, 7, v8
	s_movk_i32 s4, 0xe0
	v_and_b32_e32 v4, 32, v185
	v_and_or_b32 v3, v2, s4, v0
	v_bitop3_b32 v9, v1, v4, 48 bitop3:0x6c
	v_and_b32_e32 v10, 64, v185
	v_bfe_u32 v12, v185, 2, 4
	s_movk_i32 s4, 0xf0
	v_or_b32_e32 v1, v9, v10
	v_and_or_b32 v2, v2, s4, v12
	s_add_u32 s3, s76, 0x400000
	v_lshl_or_b32 v130, v2, 11, v1
	v_lshrrev_b32_e32 v2, 3, v185
	s_movk_i32 s4, 0x60
	s_addc_u32 s30, s77, 0
	v_and_or_b32 v0, v2, s4, v0
	s_movk_i32 s4, 0x70
	s_ashr_i32 s33, s2, 31
	v_lshl_or_b32 v132, v0, 11, v1
	v_and_or_b32 v0, v2, s4, v12
	s_lshr_b32 s4, s33, 29
	s_add_i32 s4, s2, s4
	s_lshr_b32 s10, s5, 6
	s_ashr_i32 s6, s4, 3
	s_and_b32 s4, s4, -8
	s_lshr_b32 s12, s5, 8
	s_lshl_b32 s31, s10, 10
	s_sub_i32 s4, s2, s4
	s_cmp_lt_i32 s4, 0
	s_movk_i32 s34, 0xb1
	s_cselect_b32 s7, s34, 0xb0
	s_mul_i32 s4, s4, s7
	s_add_i32 s4, s4, s6
	s_mul_hi_i32 s6, s4, 0x2e8ba2e9
	s_lshr_b32 s7, s6, 31
	s_ashr_i32 s6, s6, 4
	s_add_i32 s6, s6, s7
	s_lshl_b32 s7, s6, 2
	s_mulk_i32 s6, 0x58
	s_sub_i32 s6, s4, s6
	s_bfe_i32 s4, s6, 0x80000
	s_bfe_u32 s4, s4, 0x2000d
	s_add_i32 s8, s6, s4
	s_bfe_i32 s4, s8, 0x80000
	s_and_b32 s8, s8, 0xfc
	s_sub_i32 s6, s6, s8
	s_sext_i32_i16 s4, s4
	s_sext_i32_i8 s6, s6
	s_lshr_b32 s4, s4, 2
	s_add_i32 s22, s7, s6
	s_ashr_i32 s23, s22, 31
	s_bfe_i64 s[8:9], s[4:5], 0x100000
	s_lshl_b64 s[6:7], s[22:23], 19
	s_lshl_b64 s[8:9], s[8:9], 19
	s_add_u32 s26, s3, s8
	s_addc_u32 s27, s30, s9
	s_add_i32 s23, s31, 0
	s_add_i32 m0, s23, 0x10000
	v_lshl_or_b32 v128, v3, 11, v1
	global_load_lds_dwordx4 v132, s[26:27]
	s_add_i32 m0, s23, 0x12000
	s_add_u32 s8, s26, 0x40000
	global_load_lds_dwordx4 v128, s[26:27]
	s_addc_u32 s9, s27, 0
	s_add_i32 m0, s23, 0x14000
	v_lshl_or_b32 v134, v0, 11, v1
	global_load_lds_dwordx4 v132, s[8:9]
	s_add_i32 m0, s23, 0x16000
	s_add_u32 s24, s82, s6
	s_addc_u32 s25, s83, s7
	s_add_i32 s35, s23, 0x2000
	global_load_lds_dwordx4 v128, s[8:9]
	s_mov_b32 m0, s23
	s_add_u32 s6, s24, 0x40000
	global_load_lds_dwordx4 v134, s[24:25]
	s_mov_b32 m0, s35
	s_addc_u32 s7, s25, 0
	s_add_i32 s36, s23, 0x4000
	global_load_lds_dwordx4 v130, s[24:25]
	s_mov_b32 m0, s36
	s_add_i32 s37, s23, 0x6000
	global_load_lds_dwordx4 v134, s[6:7]
	s_mov_b32 m0, s37
	v_mov_b32_e32 v133, 0
	global_load_lds_dwordx4 v130, s[6:7]
	v_mov_b32_e32 v129, v133
	v_mov_b32_e32 v135, v133
	v_mov_b32_e32 v131, v133
	s_cmp_eq_u32 s12, 1
	s_mov_b32 s38, 0
	v_lshl_add_u64 v[6:7], s[26:27], 0, v[132:133]
	v_lshl_add_u64 v[4:5], s[26:27], 0, v[128:129]
	v_lshl_add_u64 v[0:1], s[24:25], 0, v[134:135]
	s_cselect_b64 s[6:7], -1, 0
	s_cmp_lg_u32 s12, 1
	v_lshl_add_u64 v[2:3], s[24:25], 0, v[130:131]
	s_cbranch_scc1 .LBB0_1969
	s_barrier
